# phase 1: half of the blocks (blockIdx bit 3) run the weight transposes before the layer-0 row norm, so HBM-streaming norm work and latency-bound transposes overlap across blocks
# baseline (speedup 1.0000x reference)
.LBB0_94:
	s_cmp_gt_i32 s44, 1
	s_cselect_b64 s[2:3], -1, 0
	s_cmp_lt_i32 s45, 2
	s_cselect_b64 s[4:5], -1, 0
	s_or_b64 s[2:3], s[2:3], s[4:5]
	s_and_b64 vcc, exec, s[2:3]
	s_cbranch_vccnz .LBB0_295
	s_mov_b32 s80, 0
	s_bitcmp1_b32 s22, 3
	s_cbranch_scc0 .Lp1_norm_first
	s_mov_b32 s80, 1
	v_mbcnt_hi_u32_b32 v32, -1, v210
	s_mov_b64 s[4:5], exec
	s_branch .LBB0_100
.Lp1_norm_first:
	s_lshl_b32 s96, s22, 3
	s_lshr_b32 s97, s70, 6
	s_add_u32 s96, s96, s97
	s_lshl_b32 s97, s96, 4
	s_cmpk_ge_u32 s97, 0x8000
	s_cbranch_scc1 .Lnp1_done
	s_load_dwordx2 s[88:89], s[0:1], 0x0
	s_load_dwordx2 s[90:91], s[0:1], 0x18
	s_load_dwordx2 s[92:93], s[0:1], 0x140
	s_load_dwordx2 s[94:95], s[0:1], 0x158
	v_mbcnt_hi_u32_b32 v0, -1, v210
	v_lshlrev_b32_e32 v1, 4, v0
	s_waitcnt lgkmcnt(0)
	s_add_u32 s90, s90, 0
	s_addc_u32 s91, s91, 0
	global_load_dwordx4 v[112:115], v1, s[90:91] nt
	global_load_dwordx4 v[116:119], v1, s[90:91] offset:1024 nt
	global_load_dwordx4 v[120:123], v1, s[90:91] offset:2048 nt
	global_load_dwordx4 v[124:127], v1, s[90:91] offset:3072 nt
	s_lshr_b32 s98, s97, 12
	s_add_u32 s98, s98, 0
	s_mul_i32 s98, s98, 0x3000
	s_add_u32 s92, s92, s98
	s_addc_u32 s93, s93, 0
	global_load_dwordx4 v[144:147], v1, s[92:93] nt
	global_load_dwordx4 v[148:151], v1, s[92:93] offset:1024 nt
	global_load_dwordx4 v[152:155], v1, s[92:93] offset:2048 nt
	global_load_dwordx4 v[156:159], v1, s[92:93] offset:3072 nt
	s_add_u32 s92, s92, 0x1000
	s_addc_u32 s93, s93, 0
	global_load_dwordx4 v[128:131], v1, s[92:93] nt
	global_load_dwordx4 v[132:135], v1, s[92:93] offset:1024 nt
	global_load_dwordx4 v[136:139], v1, s[92:93] offset:2048 nt
	global_load_dwordx4 v[140:143], v1, s[92:93] offset:3072 nt
	s_load_dwordx2 s[90:91], s[0:1], 0x210
	s_load_dwordx2 s[92:93], s[0:1], 0x218
	s_waitcnt vmcnt(0) lgkmcnt(0)
	v_pk_add_f32 v[128:129], v[128:129], 1.0 op_sel_hi:[1,0]
	v_pk_add_f32 v[130:131], v[130:131], 1.0 op_sel_hi:[1,0]
	v_pk_add_f32 v[132:133], v[132:133], 1.0 op_sel_hi:[1,0]
	v_pk_add_f32 v[134:135], v[134:135], 1.0 op_sel_hi:[1,0]
	v_pk_add_f32 v[136:137], v[136:137], 1.0 op_sel_hi:[1,0]
	v_pk_add_f32 v[138:139], v[138:139], 1.0 op_sel_hi:[1,0]
	v_pk_add_f32 v[140:141], v[140:141], 1.0 op_sel_hi:[1,0]
	v_pk_add_f32 v[142:143], v[142:143], 1.0 op_sel_hi:[1,0]
	s_add_u32 s98, s97, 0
	s_lshl_b32 s98, s98, 12
	v_add_u32_e32 v3, s98, v1
	global_load_dwordx4 v[16:19], v3, s[88:89] nt
	global_load_dwordx4 v[20:23], v3, s[88:89] offset:1024 nt
	global_load_dwordx4 v[24:27], v3, s[88:89] offset:2048 nt
	global_load_dwordx4 v[28:31], v3, s[88:89] offset:3072 nt
	s_add_u32 s98, s97, 1
	s_lshl_b32 s98, s98, 12
	v_add_u32_e32 v3, s98, v1
	global_load_dwordx4 v[32:35], v3, s[88:89] nt
	global_load_dwordx4 v[36:39], v3, s[88:89] offset:1024 nt
	global_load_dwordx4 v[40:43], v3, s[88:89] offset:2048 nt
	global_load_dwordx4 v[44:47], v3, s[88:89] offset:3072 nt
	s_add_u32 s98, s97, 2
	s_lshl_b32 s98, s98, 12
	v_add_u32_e32 v3, s98, v1
	global_load_dwordx4 v[48:51], v3, s[88:89] nt
	global_load_dwordx4 v[52:55], v3, s[88:89] offset:1024 nt
	global_load_dwordx4 v[56:59], v3, s[88:89] offset:2048 nt
	global_load_dwordx4 v[60:63], v3, s[88:89] offset:3072 nt
	s_add_u32 s98, s97, 3
	s_lshl_b32 s98, s98, 12
	v_add_u32_e32 v3, s98, v1
	global_load_dwordx4 v[64:67], v3, s[88:89] nt
	global_load_dwordx4 v[68:71], v3, s[88:89] offset:1024 nt
	global_load_dwordx4 v[72:75], v3, s[88:89] offset:2048 nt
	global_load_dwordx4 v[76:79], v3, s[88:89] offset:3072 nt
	s_add_u32 s98, s97, 4
	s_lshl_b32 s98, s98, 12
	v_add_u32_e32 v3, s98, v1
	global_load_dwordx4 v[80:83], v3, s[88:89] nt
	global_load_dwordx4 v[84:87], v3, s[88:89] offset:1024 nt
	global_load_dwordx4 v[88:91], v3, s[88:89] offset:2048 nt
	global_load_dwordx4 v[92:95], v3, s[88:89] offset:3072 nt
	s_add_u32 s98, s97, 5
	s_lshl_b32 s98, s98, 12
	v_add_u32_e32 v3, s98, v1
	global_load_dwordx4 v[96:99], v3, s[88:89] nt
	global_load_dwordx4 v[100:103], v3, s[88:89] offset:1024 nt
	global_load_dwordx4 v[104:107], v3, s[88:89] offset:2048 nt
	global_load_dwordx4 v[108:111], v3, s[88:89] offset:3072 nt
	s_waitcnt vmcnt(20)
	v_mul_f32_e32 v4, v16, v16
	v_fma_f32 v4, v17, v17, v4
	v_fma_f32 v4, v18, v18, v4
	v_fma_f32 v4, v19, v19, v4
	v_fma_f32 v4, v20, v20, v4
	v_fma_f32 v4, v21, v21, v4
	v_fma_f32 v4, v22, v22, v4
	v_fma_f32 v4, v23, v23, v4
	v_fma_f32 v4, v24, v24, v4
	v_fma_f32 v4, v25, v25, v4
	v_fma_f32 v4, v26, v26, v4
	v_fma_f32 v4, v27, v27, v4
	v_fma_f32 v4, v28, v28, v4
	v_fma_f32 v4, v29, v29, v4
	v_fma_f32 v4, v30, v30, v4
	v_fma_f32 v4, v31, v31, v4
	s_nop 1
	v_add_f32_dpp v5, v4, v4 quad_perm:[1,0,3,2] row_mask:0xf bank_mask:0xf
	s_nop 1
	v_add_f32_dpp v4, v5, v5 quad_perm:[2,3,0,1] row_mask:0xf bank_mask:0xf
	s_nop 1
	v_add_f32_dpp v5, v4, v4 row_half_mirror row_mask:0xf bank_mask:0xf
	s_nop 1
	v_add_f32_dpp v4, v5, v5 row_mirror row_mask:0xf bank_mask:0xf
	s_nop 1
	v_readlane_b32 s98, v4, 0
	v_readlane_b32 s99, v4, 16
	s_nop 3
	v_mov_b32_e32 v5, s98
	v_add_f32_e32 v5, s99, v5
	v_readlane_b32 s98, v4, 32
	v_readlane_b32 s99, v4, 48
	s_nop 3
	v_add_f32_e32 v5, s98, v5
	v_add_f32_e32 v5, s99, v5
	v_mul_f32_e32 v5, 0x3a800000, v5
	v_add_f32_e32 v5, 0x358637bd, v5
	v_rsq_f32_e32 v6, v5
	s_nop 0
	s_add_u32 s98, s97, 0
	v_pk_mul_f32 v[16:17], v[16:17], v[6:7] op_sel_hi:[1,0]
	v_pk_mul_f32 v[18:19], v[18:19], v[6:7] op_sel_hi:[1,0]
	v_pk_mul_f32 v[20:21], v[20:21], v[6:7] op_sel_hi:[1,0]
	v_pk_mul_f32 v[22:23], v[22:23], v[6:7] op_sel_hi:[1,0]
	v_pk_mul_f32 v[24:25], v[24:25], v[6:7] op_sel_hi:[1,0]
	v_pk_mul_f32 v[26:27], v[26:27], v[6:7] op_sel_hi:[1,0]
	v_pk_mul_f32 v[28:29], v[28:29], v[6:7] op_sel_hi:[1,0]
	v_pk_mul_f32 v[30:31], v[30:31], v[6:7] op_sel_hi:[1,0]
	v_pk_mul_f32 v[16:17], v[16:17], v[112:113]
	v_pk_mul_f32 v[18:19], v[18:19], v[114:115]
	v_pk_mul_f32 v[20:21], v[20:21], v[116:117]
	v_pk_mul_f32 v[22:23], v[22:23], v[118:119]
	v_pk_mul_f32 v[24:25], v[24:25], v[120:121]
	v_pk_mul_f32 v[26:27], v[26:27], v[122:123]
	v_pk_mul_f32 v[28:29], v[28:29], v[124:125]
	v_pk_mul_f32 v[30:31], v[30:31], v[126:127]
	v_pk_fma_f32 v[16:17], v[16:17], v[128:129], v[144:145]
	v_pk_fma_f32 v[18:19], v[18:19], v[130:131], v[146:147]
	v_pk_fma_f32 v[20:21], v[20:21], v[132:133], v[148:149]
	v_pk_fma_f32 v[22:23], v[22:23], v[134:135], v[150:151]
	v_pk_fma_f32 v[24:25], v[24:25], v[136:137], v[152:153]
	v_pk_fma_f32 v[26:27], v[26:27], v[138:139], v[154:155]
	v_pk_fma_f32 v[28:29], v[28:29], v[140:141], v[156:157]
	v_pk_fma_f32 v[30:31], v[30:31], v[142:143], v[158:159]
	v_cvt_pk_bf16_f32 v16, v16, v17
	v_cvt_pk_bf16_f32 v17, v18, v19
	v_cvt_pk_bf16_f32 v18, v20, v21
	v_cvt_pk_bf16_f32 v19, v22, v23
	v_cvt_pk_bf16_f32 v20, v24, v25
	v_cvt_pk_bf16_f32 v21, v26, v27
	v_cvt_pk_bf16_f32 v22, v28, v29
	v_cvt_pk_bf16_f32 v23, v30, v31
	s_lshl_b32 s99, s98, 11
	v_lshl_add_u32 v8, v0, 3, s99
	global_store_dwordx2 v8, v[16:17], s[94:95]
	global_store_dwordx2 v8, v[18:19], s[94:95] offset:512
	global_store_dwordx2 v8, v[20:21], s[94:95] offset:1024
	global_store_dwordx2 v8, v[22:23], s[94:95] offset:1536
	s_lshl_b32 s99, s98, 2
	v_mov_b32_e32 v9, s99
	v_mov_b32_e32 v10, 0
	v_cmp_eq_u32_e32 vcc, 0, v0
	s_and_saveexec_b64 s[98:99], vcc
	global_store_dword v9, v10, s[90:91]
	global_store_dword v9, v10, s[92:93]
	s_or_b64 exec, exec, s[98:99]
	s_add_u32 s98, s97, 6
	s_lshl_b32 s98, s98, 12
	v_add_u32_e32 v3, s98, v1
	global_load_dwordx4 v[16:19], v3, s[88:89] nt
	global_load_dwordx4 v[20:23], v3, s[88:89] offset:1024 nt
	global_load_dwordx4 v[24:27], v3, s[88:89] offset:2048 nt
	global_load_dwordx4 v[28:31], v3, s[88:89] offset:3072 nt
	s_waitcnt vmcnt(26)
	v_mul_f32_e32 v4, v32, v32
	v_fma_f32 v4, v33, v33, v4
	v_fma_f32 v4, v34, v34, v4
	v_fma_f32 v4, v35, v35, v4
	v_fma_f32 v4, v36, v36, v4
	v_fma_f32 v4, v37, v37, v4
	v_fma_f32 v4, v38, v38, v4
	v_fma_f32 v4, v39, v39, v4
	v_fma_f32 v4, v40, v40, v4
	v_fma_f32 v4, v41, v41, v4
	v_fma_f32 v4, v42, v42, v4
	v_fma_f32 v4, v43, v43, v4
	v_fma_f32 v4, v44, v44, v4
	v_fma_f32 v4, v45, v45, v4
	v_fma_f32 v4, v46, v46, v4
	v_fma_f32 v4, v47, v47, v4
	s_nop 1
	v_add_f32_dpp v5, v4, v4 quad_perm:[1,0,3,2] row_mask:0xf bank_mask:0xf
	s_nop 1
	v_add_f32_dpp v4, v5, v5 quad_perm:[2,3,0,1] row_mask:0xf bank_mask:0xf
	s_nop 1
	v_add_f32_dpp v5, v4, v4 row_half_mirror row_mask:0xf bank_mask:0xf
	s_nop 1
	v_add_f32_dpp v4, v5, v5 row_mirror row_mask:0xf bank_mask:0xf
	s_nop 1
	v_readlane_b32 s98, v4, 0
	v_readlane_b32 s99, v4, 16
	s_nop 3
	v_mov_b32_e32 v5, s98
	v_add_f32_e32 v5, s99, v5
	v_readlane_b32 s98, v4, 32
	v_readlane_b32 s99, v4, 48
	s_nop 3
	v_add_f32_e32 v5, s98, v5
	v_add_f32_e32 v5, s99, v5
	v_mul_f32_e32 v5, 0x3a800000, v5
	v_add_f32_e32 v5, 0x358637bd, v5
	v_rsq_f32_e32 v6, v5
	s_nop 0
	s_add_u32 s98, s97, 1
	v_pk_mul_f32 v[32:33], v[32:33], v[6:7] op_sel_hi:[1,0]
	v_pk_mul_f32 v[34:35], v[34:35], v[6:7] op_sel_hi:[1,0]
	v_pk_mul_f32 v[36:37], v[36:37], v[6:7] op_sel_hi:[1,0]
	v_pk_mul_f32 v[38:39], v[38:39], v[6:7] op_sel_hi:[1,0]
	v_pk_mul_f32 v[40:41], v[40:41], v[6:7] op_sel_hi:[1,0]
	v_pk_mul_f32 v[42:43], v[42:43], v[6:7] op_sel_hi:[1,0]
	v_pk_mul_f32 v[44:45], v[44:45], v[6:7] op_sel_hi:[1,0]
	v_pk_mul_f32 v[46:47], v[46:47], v[6:7] op_sel_hi:[1,0]
	v_pk_mul_f32 v[32:33], v[32:33], v[112:113]
	v_pk_mul_f32 v[34:35], v[34:35], v[114:115]
	v_pk_mul_f32 v[36:37], v[36:37], v[116:117]
	v_pk_mul_f32 v[38:39], v[38:39], v[118:119]
	v_pk_mul_f32 v[40:41], v[40:41], v[120:121]
	v_pk_mul_f32 v[42:43], v[42:43], v[122:123]
	v_pk_mul_f32 v[44:45], v[44:45], v[124:125]
	v_pk_mul_f32 v[46:47], v[46:47], v[126:127]
	v_pk_fma_f32 v[32:33], v[32:33], v[128:129], v[144:145]
	v_pk_fma_f32 v[34:35], v[34:35], v[130:131], v[146:147]
	v_pk_fma_f32 v[36:37], v[36:37], v[132:133], v[148:149]
	v_pk_fma_f32 v[38:39], v[38:39], v[134:135], v[150:151]
	v_pk_fma_f32 v[40:41], v[40:41], v[136:137], v[152:153]
	v_pk_fma_f32 v[42:43], v[42:43], v[138:139], v[154:155]
	v_pk_fma_f32 v[44:45], v[44:45], v[140:141], v[156:157]
	v_pk_fma_f32 v[46:47], v[46:47], v[142:143], v[158:159]
	v_cvt_pk_bf16_f32 v32, v32, v33
	v_cvt_pk_bf16_f32 v33, v34, v35
	v_cvt_pk_bf16_f32 v34, v36, v37
	v_cvt_pk_bf16_f32 v35, v38, v39
	v_cvt_pk_bf16_f32 v36, v40, v41
	v_cvt_pk_bf16_f32 v37, v42, v43
	v_cvt_pk_bf16_f32 v38, v44, v45
	v_cvt_pk_bf16_f32 v39, v46, v47
	s_lshl_b32 s99, s98, 11
	v_lshl_add_u32 v8, v0, 3, s99
	global_store_dwordx2 v8, v[32:33], s[94:95]
	global_store_dwordx2 v8, v[34:35], s[94:95] offset:512
	global_store_dwordx2 v8, v[36:37], s[94:95] offset:1024
	global_store_dwordx2 v8, v[38:39], s[94:95] offset:1536
	s_lshl_b32 s99, s98, 2
	v_mov_b32_e32 v9, s99
	v_mov_b32_e32 v10, 0
	v_cmp_eq_u32_e32 vcc, 0, v0
	s_and_saveexec_b64 s[98:99], vcc
	global_store_dword v9, v10, s[90:91]
	global_store_dword v9, v10, s[92:93]
	s_or_b64 exec, exec, s[98:99]
	s_add_u32 s98, s97, 7
	s_lshl_b32 s98, s98, 12
	v_add_u32_e32 v3, s98, v1
	global_load_dwordx4 v[32:35], v3, s[88:89] nt
	global_load_dwordx4 v[36:39], v3, s[88:89] offset:1024 nt
	global_load_dwordx4 v[40:43], v3, s[88:89] offset:2048 nt
	global_load_dwordx4 v[44:47], v3, s[88:89] offset:3072 nt
	s_waitcnt vmcnt(32)
	v_mul_f32_e32 v4, v48, v48
	v_fma_f32 v4, v49, v49, v4
	v_fma_f32 v4, v50, v50, v4
	v_fma_f32 v4, v51, v51, v4
	v_fma_f32 v4, v52, v52, v4
	v_fma_f32 v4, v53, v53, v4
	v_fma_f32 v4, v54, v54, v4
	v_fma_f32 v4, v55, v55, v4
	v_fma_f32 v4, v56, v56, v4
	v_fma_f32 v4, v57, v57, v4
	v_fma_f32 v4, v58, v58, v4
	v_fma_f32 v4, v59, v59, v4
	v_fma_f32 v4, v60, v60, v4
	v_fma_f32 v4, v61, v61, v4
	v_fma_f32 v4, v62, v62, v4
	v_fma_f32 v4, v63, v63, v4
	s_nop 1
	v_add_f32_dpp v5, v4, v4 quad_perm:[1,0,3,2] row_mask:0xf bank_mask:0xf
	s_nop 1
	v_add_f32_dpp v4, v5, v5 quad_perm:[2,3,0,1] row_mask:0xf bank_mask:0xf
	s_nop 1
	v_add_f32_dpp v5, v4, v4 row_half_mirror row_mask:0xf bank_mask:0xf
	s_nop 1
	v_add_f32_dpp v4, v5, v5 row_mirror row_mask:0xf bank_mask:0xf
	s_nop 1
	v_readlane_b32 s98, v4, 0
	v_readlane_b32 s99, v4, 16
	s_nop 3
	v_mov_b32_e32 v5, s98
	v_add_f32_e32 v5, s99, v5
	v_readlane_b32 s98, v4, 32
	v_readlane_b32 s99, v4, 48
	s_nop 3
	v_add_f32_e32 v5, s98, v5
	v_add_f32_e32 v5, s99, v5
	v_mul_f32_e32 v5, 0x3a800000, v5
	v_add_f32_e32 v5, 0x358637bd, v5
	v_rsq_f32_e32 v6, v5
	s_nop 0
	s_add_u32 s98, s97, 2
	v_pk_mul_f32 v[48:49], v[48:49], v[6:7] op_sel_hi:[1,0]
	v_pk_mul_f32 v[50:51], v[50:51], v[6:7] op_sel_hi:[1,0]
	v_pk_mul_f32 v[52:53], v[52:53], v[6:7] op_sel_hi:[1,0]
	v_pk_mul_f32 v[54:55], v[54:55], v[6:7] op_sel_hi:[1,0]
	v_pk_mul_f32 v[56:57], v[56:57], v[6:7] op_sel_hi:[1,0]
	v_pk_mul_f32 v[58:59], v[58:59], v[6:7] op_sel_hi:[1,0]
	v_pk_mul_f32 v[60:61], v[60:61], v[6:7] op_sel_hi:[1,0]
	v_pk_mul_f32 v[62:63], v[62:63], v[6:7] op_sel_hi:[1,0]
	v_pk_mul_f32 v[48:49], v[48:49], v[112:113]
	v_pk_mul_f32 v[50:51], v[50:51], v[114:115]
	v_pk_mul_f32 v[52:53], v[52:53], v[116:117]
	v_pk_mul_f32 v[54:55], v[54:55], v[118:119]
	v_pk_mul_f32 v[56:57], v[56:57], v[120:121]
	v_pk_mul_f32 v[58:59], v[58:59], v[122:123]
	v_pk_mul_f32 v[60:61], v[60:61], v[124:125]
	v_pk_mul_f32 v[62:63], v[62:63], v[126:127]
	v_pk_fma_f32 v[48:49], v[48:49], v[128:129], v[144:145]
	v_pk_fma_f32 v[50:51], v[50:51], v[130:131], v[146:147]
	v_pk_fma_f32 v[52:53], v[52:53], v[132:133], v[148:149]
	v_pk_fma_f32 v[54:55], v[54:55], v[134:135], v[150:151]
	v_pk_fma_f32 v[56:57], v[56:57], v[136:137], v[152:153]
	v_pk_fma_f32 v[58:59], v[58:59], v[138:139], v[154:155]
	v_pk_fma_f32 v[60:61], v[60:61], v[140:141], v[156:157]
	v_pk_fma_f32 v[62:63], v[62:63], v[142:143], v[158:159]
	v_cvt_pk_bf16_f32 v48, v48, v49
	v_cvt_pk_bf16_f32 v49, v50, v51
	v_cvt_pk_bf16_f32 v50, v52, v53
	v_cvt_pk_bf16_f32 v51, v54, v55
	v_cvt_pk_bf16_f32 v52, v56, v57
	v_cvt_pk_bf16_f32 v53, v58, v59
	v_cvt_pk_bf16_f32 v54, v60, v61
	v_cvt_pk_bf16_f32 v55, v62, v63
	s_lshl_b32 s99, s98, 11
	v_lshl_add_u32 v8, v0, 3, s99
	global_store_dwordx2 v8, v[48:49], s[94:95]
	global_store_dwordx2 v8, v[50:51], s[94:95] offset:512
	global_store_dwordx2 v8, v[52:53], s[94:95] offset:1024
	global_store_dwordx2 v8, v[54:55], s[94:95] offset:1536
	s_lshl_b32 s99, s98, 2
	v_mov_b32_e32 v9, s99
	v_mov_b32_e32 v10, 0
	v_cmp_eq_u32_e32 vcc, 0, v0
	s_and_saveexec_b64 s[98:99], vcc
	global_store_dword v9, v10, s[90:91]
	global_store_dword v9, v10, s[92:93]
	s_or_b64 exec, exec, s[98:99]
	s_add_u32 s98, s97, 8
	s_lshl_b32 s98, s98, 12
	v_add_u32_e32 v3, s98, v1
	global_load_dwordx4 v[48:51], v3, s[88:89] nt
	global_load_dwordx4 v[52:55], v3, s[88:89] offset:1024 nt
	global_load_dwordx4 v[56:59], v3, s[88:89] offset:2048 nt
	global_load_dwordx4 v[60:63], v3, s[88:89] offset:3072 nt
	s_waitcnt vmcnt(38)
	v_mul_f32_e32 v4, v64, v64
	v_fma_f32 v4, v65, v65, v4
	v_fma_f32 v4, v66, v66, v4
	v_fma_f32 v4, v67, v67, v4
	v_fma_f32 v4, v68, v68, v4
	v_fma_f32 v4, v69, v69, v4
	v_fma_f32 v4, v70, v70, v4
	v_fma_f32 v4, v71, v71, v4
	v_fma_f32 v4, v72, v72, v4
	v_fma_f32 v4, v73, v73, v4
	v_fma_f32 v4, v74, v74, v4
	v_fma_f32 v4, v75, v75, v4
	v_fma_f32 v4, v76, v76, v4
	v_fma_f32 v4, v77, v77, v4
	v_fma_f32 v4, v78, v78, v4
	v_fma_f32 v4, v79, v79, v4
	s_nop 1
	v_add_f32_dpp v5, v4, v4 quad_perm:[1,0,3,2] row_mask:0xf bank_mask:0xf
	s_nop 1
	v_add_f32_dpp v4, v5, v5 quad_perm:[2,3,0,1] row_mask:0xf bank_mask:0xf
	s_nop 1
	v_add_f32_dpp v5, v4, v4 row_half_mirror row_mask:0xf bank_mask:0xf
	s_nop 1
	v_add_f32_dpp v4, v5, v5 row_mirror row_mask:0xf bank_mask:0xf
	s_nop 1
	v_readlane_b32 s98, v4, 0
	v_readlane_b32 s99, v4, 16
	s_nop 3
	v_mov_b32_e32 v5, s98
	v_add_f32_e32 v5, s99, v5
	v_readlane_b32 s98, v4, 32
	v_readlane_b32 s99, v4, 48
	s_nop 3
	v_add_f32_e32 v5, s98, v5
	v_add_f32_e32 v5, s99, v5
	v_mul_f32_e32 v5, 0x3a800000, v5
	v_add_f32_e32 v5, 0x358637bd, v5
	v_rsq_f32_e32 v6, v5
	s_nop 0
	s_add_u32 s98, s97, 3
	v_pk_mul_f32 v[64:65], v[64:65], v[6:7] op_sel_hi:[1,0]
	v_pk_mul_f32 v[66:67], v[66:67], v[6:7] op_sel_hi:[1,0]
	v_pk_mul_f32 v[68:69], v[68:69], v[6:7] op_sel_hi:[1,0]
	v_pk_mul_f32 v[70:71], v[70:71], v[6:7] op_sel_hi:[1,0]
	v_pk_mul_f32 v[72:73], v[72:73], v[6:7] op_sel_hi:[1,0]
	v_pk_mul_f32 v[74:75], v[74:75], v[6:7] op_sel_hi:[1,0]
	v_pk_mul_f32 v[76:77], v[76:77], v[6:7] op_sel_hi:[1,0]
	v_pk_mul_f32 v[78:79], v[78:79], v[6:7] op_sel_hi:[1,0]
	v_pk_mul_f32 v[64:65], v[64:65], v[112:113]
	v_pk_mul_f32 v[66:67], v[66:67], v[114:115]
	v_pk_mul_f32 v[68:69], v[68:69], v[116:117]
	v_pk_mul_f32 v[70:71], v[70:71], v[118:119]
	v_pk_mul_f32 v[72:73], v[72:73], v[120:121]
	v_pk_mul_f32 v[74:75], v[74:75], v[122:123]
	v_pk_mul_f32 v[76:77], v[76:77], v[124:125]
	v_pk_mul_f32 v[78:79], v[78:79], v[126:127]
	v_pk_fma_f32 v[64:65], v[64:65], v[128:129], v[144:145]
	v_pk_fma_f32 v[66:67], v[66:67], v[130:131], v[146:147]
	v_pk_fma_f32 v[68:69], v[68:69], v[132:133], v[148:149]
	v_pk_fma_f32 v[70:71], v[70:71], v[134:135], v[150:151]
	v_pk_fma_f32 v[72:73], v[72:73], v[136:137], v[152:153]
	v_pk_fma_f32 v[74:75], v[74:75], v[138:139], v[154:155]
	v_pk_fma_f32 v[76:77], v[76:77], v[140:141], v[156:157]
	v_pk_fma_f32 v[78:79], v[78:79], v[142:143], v[158:159]
	v_cvt_pk_bf16_f32 v64, v64, v65
	v_cvt_pk_bf16_f32 v65, v66, v67
	v_cvt_pk_bf16_f32 v66, v68, v69
	v_cvt_pk_bf16_f32 v67, v70, v71
	v_cvt_pk_bf16_f32 v68, v72, v73
	v_cvt_pk_bf16_f32 v69, v74, v75
	v_cvt_pk_bf16_f32 v70, v76, v77
	v_cvt_pk_bf16_f32 v71, v78, v79
	s_lshl_b32 s99, s98, 11
	v_lshl_add_u32 v8, v0, 3, s99
	global_store_dwordx2 v8, v[64:65], s[94:95]
	global_store_dwordx2 v8, v[66:67], s[94:95] offset:512
	global_store_dwordx2 v8, v[68:69], s[94:95] offset:1024
	global_store_dwordx2 v8, v[70:71], s[94:95] offset:1536
	s_lshl_b32 s99, s98, 2
	v_mov_b32_e32 v9, s99
	v_mov_b32_e32 v10, 0
	v_cmp_eq_u32_e32 vcc, 0, v0
	s_and_saveexec_b64 s[98:99], vcc
	global_store_dword v9, v10, s[90:91]
	global_store_dword v9, v10, s[92:93]
	s_or_b64 exec, exec, s[98:99]
	s_add_u32 s98, s97, 9
	s_lshl_b32 s98, s98, 12
	v_add_u32_e32 v3, s98, v1
	global_load_dwordx4 v[64:67], v3, s[88:89] nt
	global_load_dwordx4 v[68:71], v3, s[88:89] offset:1024 nt
	global_load_dwordx4 v[72:75], v3, s[88:89] offset:2048 nt
	global_load_dwordx4 v[76:79], v3, s[88:89] offset:3072 nt
	s_waitcnt vmcnt(44)
	v_mul_f32_e32 v4, v80, v80
	v_fma_f32 v4, v81, v81, v4
	v_fma_f32 v4, v82, v82, v4
	v_fma_f32 v4, v83, v83, v4
	v_fma_f32 v4, v84, v84, v4
	v_fma_f32 v4, v85, v85, v4
	v_fma_f32 v4, v86, v86, v4
	v_fma_f32 v4, v87, v87, v4
	v_fma_f32 v4, v88, v88, v4
	v_fma_f32 v4, v89, v89, v4
	v_fma_f32 v4, v90, v90, v4
	v_fma_f32 v4, v91, v91, v4
	v_fma_f32 v4, v92, v92, v4
	v_fma_f32 v4, v93, v93, v4
	v_fma_f32 v4, v94, v94, v4
	v_fma_f32 v4, v95, v95, v4
	s_nop 1
	v_add_f32_dpp v5, v4, v4 quad_perm:[1,0,3,2] row_mask:0xf bank_mask:0xf
	s_nop 1
	v_add_f32_dpp v4, v5, v5 quad_perm:[2,3,0,1] row_mask:0xf bank_mask:0xf
	s_nop 1
	v_add_f32_dpp v5, v4, v4 row_half_mirror row_mask:0xf bank_mask:0xf
	s_nop 1
	v_add_f32_dpp v4, v5, v5 row_mirror row_mask:0xf bank_mask:0xf
	s_nop 1
	v_readlane_b32 s98, v4, 0
	v_readlane_b32 s99, v4, 16
	s_nop 3
	v_mov_b32_e32 v5, s98
	v_add_f32_e32 v5, s99, v5
	v_readlane_b32 s98, v4, 32
	v_readlane_b32 s99, v4, 48
	s_nop 3
	v_add_f32_e32 v5, s98, v5
	v_add_f32_e32 v5, s99, v5
	v_mul_f32_e32 v5, 0x3a800000, v5
	v_add_f32_e32 v5, 0x358637bd, v5
	v_rsq_f32_e32 v6, v5
	s_nop 0
	s_add_u32 s98, s97, 4
	v_pk_mul_f32 v[80:81], v[80:81], v[6:7] op_sel_hi:[1,0]
	v_pk_mul_f32 v[82:83], v[82:83], v[6:7] op_sel_hi:[1,0]
	v_pk_mul_f32 v[84:85], v[84:85], v[6:7] op_sel_hi:[1,0]
	v_pk_mul_f32 v[86:87], v[86:87], v[6:7] op_sel_hi:[1,0]
	v_pk_mul_f32 v[88:89], v[88:89], v[6:7] op_sel_hi:[1,0]
	v_pk_mul_f32 v[90:91], v[90:91], v[6:7] op_sel_hi:[1,0]
	v_pk_mul_f32 v[92:93], v[92:93], v[6:7] op_sel_hi:[1,0]
	v_pk_mul_f32 v[94:95], v[94:95], v[6:7] op_sel_hi:[1,0]
	v_pk_mul_f32 v[80:81], v[80:81], v[112:113]
	v_pk_mul_f32 v[82:83], v[82:83], v[114:115]
	v_pk_mul_f32 v[84:85], v[84:85], v[116:117]
	v_pk_mul_f32 v[86:87], v[86:87], v[118:119]
	v_pk_mul_f32 v[88:89], v[88:89], v[120:121]
	v_pk_mul_f32 v[90:91], v[90:91], v[122:123]
	v_pk_mul_f32 v[92:93], v[92:93], v[124:125]
	v_pk_mul_f32 v[94:95], v[94:95], v[126:127]
	v_pk_fma_f32 v[80:81], v[80:81], v[128:129], v[144:145]
	v_pk_fma_f32 v[82:83], v[82:83], v[130:131], v[146:147]
	v_pk_fma_f32 v[84:85], v[84:85], v[132:133], v[148:149]
	v_pk_fma_f32 v[86:87], v[86:87], v[134:135], v[150:151]
	v_pk_fma_f32 v[88:89], v[88:89], v[136:137], v[152:153]
	v_pk_fma_f32 v[90:91], v[90:91], v[138:139], v[154:155]
	v_pk_fma_f32 v[92:93], v[92:93], v[140:141], v[156:157]
	v_pk_fma_f32 v[94:95], v[94:95], v[142:143], v[158:159]
	v_cvt_pk_bf16_f32 v80, v80, v81
	v_cvt_pk_bf16_f32 v81, v82, v83
	v_cvt_pk_bf16_f32 v82, v84, v85
	v_cvt_pk_bf16_f32 v83, v86, v87
	v_cvt_pk_bf16_f32 v84, v88, v89
	v_cvt_pk_bf16_f32 v85, v90, v91
	v_cvt_pk_bf16_f32 v86, v92, v93
	v_cvt_pk_bf16_f32 v87, v94, v95
	s_lshl_b32 s99, s98, 11
	v_lshl_add_u32 v8, v0, 3, s99
	global_store_dwordx2 v8, v[80:81], s[94:95]
	global_store_dwordx2 v8, v[82:83], s[94:95] offset:512
	global_store_dwordx2 v8, v[84:85], s[94:95] offset:1024
	global_store_dwordx2 v8, v[86:87], s[94:95] offset:1536
	s_lshl_b32 s99, s98, 2
	v_mov_b32_e32 v9, s99
	v_mov_b32_e32 v10, 0
	v_cmp_eq_u32_e32 vcc, 0, v0
	s_and_saveexec_b64 s[98:99], vcc
	global_store_dword v9, v10, s[90:91]
	global_store_dword v9, v10, s[92:93]
	s_or_b64 exec, exec, s[98:99]
	s_add_u32 s98, s97, 10
	s_lshl_b32 s98, s98, 12
	v_add_u32_e32 v3, s98, v1
	global_load_dwordx4 v[80:83], v3, s[88:89] nt
	global_load_dwordx4 v[84:87], v3, s[88:89] offset:1024 nt
	global_load_dwordx4 v[88:91], v3, s[88:89] offset:2048 nt
	global_load_dwordx4 v[92:95], v3, s[88:89] offset:3072 nt
	s_waitcnt vmcnt(50)
	v_mul_f32_e32 v4, v96, v96
	v_fma_f32 v4, v97, v97, v4
	v_fma_f32 v4, v98, v98, v4
	v_fma_f32 v4, v99, v99, v4
	v_fma_f32 v4, v100, v100, v4
	v_fma_f32 v4, v101, v101, v4
	v_fma_f32 v4, v102, v102, v4
	v_fma_f32 v4, v103, v103, v4
	v_fma_f32 v4, v104, v104, v4
	v_fma_f32 v4, v105, v105, v4
	v_fma_f32 v4, v106, v106, v4
	v_fma_f32 v4, v107, v107, v4
	v_fma_f32 v4, v108, v108, v4
	v_fma_f32 v4, v109, v109, v4
	v_fma_f32 v4, v110, v110, v4
	v_fma_f32 v4, v111, v111, v4
	s_nop 1
	v_add_f32_dpp v5, v4, v4 quad_perm:[1,0,3,2] row_mask:0xf bank_mask:0xf
	s_nop 1
	v_add_f32_dpp v4, v5, v5 quad_perm:[2,3,0,1] row_mask:0xf bank_mask:0xf
	s_nop 1
	v_add_f32_dpp v5, v4, v4 row_half_mirror row_mask:0xf bank_mask:0xf
	s_nop 1
	v_add_f32_dpp v4, v5, v5 row_mirror row_mask:0xf bank_mask:0xf
	s_nop 1
	v_readlane_b32 s98, v4, 0
	v_readlane_b32 s99, v4, 16
	s_nop 3
	v_mov_b32_e32 v5, s98
	v_add_f32_e32 v5, s99, v5
	v_readlane_b32 s98, v4, 32
	v_readlane_b32 s99, v4, 48
	s_nop 3
	v_add_f32_e32 v5, s98, v5
	v_add_f32_e32 v5, s99, v5
	v_mul_f32_e32 v5, 0x3a800000, v5
	v_add_f32_e32 v5, 0x358637bd, v5
	v_rsq_f32_e32 v6, v5
	s_nop 0
	s_add_u32 s98, s97, 5
	v_pk_mul_f32 v[96:97], v[96:97], v[6:7] op_sel_hi:[1,0]
	v_pk_mul_f32 v[98:99], v[98:99], v[6:7] op_sel_hi:[1,0]
	v_pk_mul_f32 v[100:101], v[100:101], v[6:7] op_sel_hi:[1,0]
	v_pk_mul_f32 v[102:103], v[102:103], v[6:7] op_sel_hi:[1,0]
	v_pk_mul_f32 v[104:105], v[104:105], v[6:7] op_sel_hi:[1,0]
	v_pk_mul_f32 v[106:107], v[106:107], v[6:7] op_sel_hi:[1,0]
	v_pk_mul_f32 v[108:109], v[108:109], v[6:7] op_sel_hi:[1,0]
	v_pk_mul_f32 v[110:111], v[110:111], v[6:7] op_sel_hi:[1,0]
	v_pk_mul_f32 v[96:97], v[96:97], v[112:113]
	v_pk_mul_f32 v[98:99], v[98:99], v[114:115]
	v_pk_mul_f32 v[100:101], v[100:101], v[116:117]
	v_pk_mul_f32 v[102:103], v[102:103], v[118:119]
	v_pk_mul_f32 v[104:105], v[104:105], v[120:121]
	v_pk_mul_f32 v[106:107], v[106:107], v[122:123]
	v_pk_mul_f32 v[108:109], v[108:109], v[124:125]
	v_pk_mul_f32 v[110:111], v[110:111], v[126:127]
	v_pk_fma_f32 v[96:97], v[96:97], v[128:129], v[144:145]
	v_pk_fma_f32 v[98:99], v[98:99], v[130:131], v[146:147]
	v_pk_fma_f32 v[100:101], v[100:101], v[132:133], v[148:149]
	v_pk_fma_f32 v[102:103], v[102:103], v[134:135], v[150:151]
	v_pk_fma_f32 v[104:105], v[104:105], v[136:137], v[152:153]
	v_pk_fma_f32 v[106:107], v[106:107], v[138:139], v[154:155]
	v_pk_fma_f32 v[108:109], v[108:109], v[140:141], v[156:157]
	v_pk_fma_f32 v[110:111], v[110:111], v[142:143], v[158:159]
	v_cvt_pk_bf16_f32 v96, v96, v97
	v_cvt_pk_bf16_f32 v97, v98, v99
	v_cvt_pk_bf16_f32 v98, v100, v101
	v_cvt_pk_bf16_f32 v99, v102, v103
	v_cvt_pk_bf16_f32 v100, v104, v105
	v_cvt_pk_bf16_f32 v101, v106, v107
	v_cvt_pk_bf16_f32 v102, v108, v109
	v_cvt_pk_bf16_f32 v103, v110, v111
	s_lshl_b32 s99, s98, 11
	v_lshl_add_u32 v8, v0, 3, s99
	global_store_dwordx2 v8, v[96:97], s[94:95]
	global_store_dwordx2 v8, v[98:99], s[94:95] offset:512
	global_store_dwordx2 v8, v[100:101], s[94:95] offset:1024
	global_store_dwordx2 v8, v[102:103], s[94:95] offset:1536
	s_lshl_b32 s99, s98, 2
	v_mov_b32_e32 v9, s99
	v_mov_b32_e32 v10, 0
	v_cmp_eq_u32_e32 vcc, 0, v0
	s_and_saveexec_b64 s[98:99], vcc
	global_store_dword v9, v10, s[90:91]
	global_store_dword v9, v10, s[92:93]
	s_or_b64 exec, exec, s[98:99]
	s_add_u32 s98, s97, 11
	s_lshl_b32 s98, s98, 12
	v_add_u32_e32 v3, s98, v1
	global_load_dwordx4 v[96:99], v3, s[88:89] nt
	global_load_dwordx4 v[100:103], v3, s[88:89] offset:1024 nt
	global_load_dwordx4 v[104:107], v3, s[88:89] offset:2048 nt
	global_load_dwordx4 v[108:111], v3, s[88:89] offset:3072 nt
	s_waitcnt vmcnt(50)
	v_mul_f32_e32 v4, v16, v16
	v_fma_f32 v4, v17, v17, v4
	v_fma_f32 v4, v18, v18, v4
	v_fma_f32 v4, v19, v19, v4
	v_fma_f32 v4, v20, v20, v4
	v_fma_f32 v4, v21, v21, v4
	v_fma_f32 v4, v22, v22, v4
	v_fma_f32 v4, v23, v23, v4
	v_fma_f32 v4, v24, v24, v4
	v_fma_f32 v4, v25, v25, v4
	v_fma_f32 v4, v26, v26, v4
	v_fma_f32 v4, v27, v27, v4
	v_fma_f32 v4, v28, v28, v4
	v_fma_f32 v4, v29, v29, v4
	v_fma_f32 v4, v30, v30, v4
	v_fma_f32 v4, v31, v31, v4
	s_nop 1
	v_add_f32_dpp v5, v4, v4 quad_perm:[1,0,3,2] row_mask:0xf bank_mask:0xf
	s_nop 1
	v_add_f32_dpp v4, v5, v5 quad_perm:[2,3,0,1] row_mask:0xf bank_mask:0xf
	s_nop 1
	v_add_f32_dpp v5, v4, v4 row_half_mirror row_mask:0xf bank_mask:0xf
	s_nop 1
	v_add_f32_dpp v4, v5, v5 row_mirror row_mask:0xf bank_mask:0xf
	s_nop 1
	v_readlane_b32 s98, v4, 0
	v_readlane_b32 s99, v4, 16
	s_nop 3
	v_mov_b32_e32 v5, s98
	v_add_f32_e32 v5, s99, v5
	v_readlane_b32 s98, v4, 32
	v_readlane_b32 s99, v4, 48
	s_nop 3
	v_add_f32_e32 v5, s98, v5
	v_add_f32_e32 v5, s99, v5
	v_mul_f32_e32 v5, 0x3a800000, v5
	v_add_f32_e32 v5, 0x358637bd, v5
	v_rsq_f32_e32 v6, v5
	s_nop 0
	s_add_u32 s98, s97, 6
	v_pk_mul_f32 v[16:17], v[16:17], v[6:7] op_sel_hi:[1,0]
	v_pk_mul_f32 v[18:19], v[18:19], v[6:7] op_sel_hi:[1,0]
	v_pk_mul_f32 v[20:21], v[20:21], v[6:7] op_sel_hi:[1,0]
	v_pk_mul_f32 v[22:23], v[22:23], v[6:7] op_sel_hi:[1,0]
	v_pk_mul_f32 v[24:25], v[24:25], v[6:7] op_sel_hi:[1,0]
	v_pk_mul_f32 v[26:27], v[26:27], v[6:7] op_sel_hi:[1,0]
	v_pk_mul_f32 v[28:29], v[28:29], v[6:7] op_sel_hi:[1,0]
	v_pk_mul_f32 v[30:31], v[30:31], v[6:7] op_sel_hi:[1,0]
	v_pk_mul_f32 v[16:17], v[16:17], v[112:113]
	v_pk_mul_f32 v[18:19], v[18:19], v[114:115]
	v_pk_mul_f32 v[20:21], v[20:21], v[116:117]
	v_pk_mul_f32 v[22:23], v[22:23], v[118:119]
	v_pk_mul_f32 v[24:25], v[24:25], v[120:121]
	v_pk_mul_f32 v[26:27], v[26:27], v[122:123]
	v_pk_mul_f32 v[28:29], v[28:29], v[124:125]
	v_pk_mul_f32 v[30:31], v[30:31], v[126:127]
	v_pk_fma_f32 v[16:17], v[16:17], v[128:129], v[144:145]
	v_pk_fma_f32 v[18:19], v[18:19], v[130:131], v[146:147]
	v_pk_fma_f32 v[20:21], v[20:21], v[132:133], v[148:149]
	v_pk_fma_f32 v[22:23], v[22:23], v[134:135], v[150:151]
	v_pk_fma_f32 v[24:25], v[24:25], v[136:137], v[152:153]
	v_pk_fma_f32 v[26:27], v[26:27], v[138:139], v[154:155]
	v_pk_fma_f32 v[28:29], v[28:29], v[140:141], v[156:157]
	v_pk_fma_f32 v[30:31], v[30:31], v[142:143], v[158:159]
	v_cvt_pk_bf16_f32 v16, v16, v17
	v_cvt_pk_bf16_f32 v17, v18, v19
	v_cvt_pk_bf16_f32 v18, v20, v21
	v_cvt_pk_bf16_f32 v19, v22, v23
	v_cvt_pk_bf16_f32 v20, v24, v25
	v_cvt_pk_bf16_f32 v21, v26, v27
	v_cvt_pk_bf16_f32 v22, v28, v29
	v_cvt_pk_bf16_f32 v23, v30, v31
	s_lshl_b32 s99, s98, 11
	v_lshl_add_u32 v8, v0, 3, s99
	global_store_dwordx2 v8, v[16:17], s[94:95]
	global_store_dwordx2 v8, v[18:19], s[94:95] offset:512
	global_store_dwordx2 v8, v[20:21], s[94:95] offset:1024
	global_store_dwordx2 v8, v[22:23], s[94:95] offset:1536
	s_lshl_b32 s99, s98, 2
	v_mov_b32_e32 v9, s99
	v_mov_b32_e32 v10, 0
	v_cmp_eq_u32_e32 vcc, 0, v0
	s_and_saveexec_b64 s[98:99], vcc
	global_store_dword v9, v10, s[90:91]
	global_store_dword v9, v10, s[92:93]
	s_or_b64 exec, exec, s[98:99]
	s_add_u32 s98, s97, 12
	s_lshl_b32 s98, s98, 12
	v_add_u32_e32 v3, s98, v1
	global_load_dwordx4 v[16:19], v3, s[88:89] nt
	global_load_dwordx4 v[20:23], v3, s[88:89] offset:1024 nt
	global_load_dwordx4 v[24:27], v3, s[88:89] offset:2048 nt
	global_load_dwordx4 v[28:31], v3, s[88:89] offset:3072 nt
	s_waitcnt vmcnt(50)
	v_mul_f32_e32 v4, v32, v32
	v_fma_f32 v4, v33, v33, v4
	v_fma_f32 v4, v34, v34, v4
	v_fma_f32 v4, v35, v35, v4
	v_fma_f32 v4, v36, v36, v4
	v_fma_f32 v4, v37, v37, v4
	v_fma_f32 v4, v38, v38, v4
	v_fma_f32 v4, v39, v39, v4
	v_fma_f32 v4, v40, v40, v4
	v_fma_f32 v4, v41, v41, v4
	v_fma_f32 v4, v42, v42, v4
	v_fma_f32 v4, v43, v43, v4
	v_fma_f32 v4, v44, v44, v4
	v_fma_f32 v4, v45, v45, v4
	v_fma_f32 v4, v46, v46, v4
	v_fma_f32 v4, v47, v47, v4
	s_nop 1
	v_add_f32_dpp v5, v4, v4 quad_perm:[1,0,3,2] row_mask:0xf bank_mask:0xf
	s_nop 1
	v_add_f32_dpp v4, v5, v5 quad_perm:[2,3,0,1] row_mask:0xf bank_mask:0xf
	s_nop 1
	v_add_f32_dpp v5, v4, v4 row_half_mirror row_mask:0xf bank_mask:0xf
	s_nop 1
	v_add_f32_dpp v4, v5, v5 row_mirror row_mask:0xf bank_mask:0xf
	s_nop 1
	v_readlane_b32 s98, v4, 0
	v_readlane_b32 s99, v4, 16
	s_nop 3
	v_mov_b32_e32 v5, s98
	v_add_f32_e32 v5, s99, v5
	v_readlane_b32 s98, v4, 32
	v_readlane_b32 s99, v4, 48
	s_nop 3
	v_add_f32_e32 v5, s98, v5
	v_add_f32_e32 v5, s99, v5
	v_mul_f32_e32 v5, 0x3a800000, v5
	v_add_f32_e32 v5, 0x358637bd, v5
	v_rsq_f32_e32 v6, v5
	s_nop 0
	s_add_u32 s98, s97, 7
	v_pk_mul_f32 v[32:33], v[32:33], v[6:7] op_sel_hi:[1,0]
	v_pk_mul_f32 v[34:35], v[34:35], v[6:7] op_sel_hi:[1,0]
	v_pk_mul_f32 v[36:37], v[36:37], v[6:7] op_sel_hi:[1,0]
	v_pk_mul_f32 v[38:39], v[38:39], v[6:7] op_sel_hi:[1,0]
	v_pk_mul_f32 v[40:41], v[40:41], v[6:7] op_sel_hi:[1,0]
	v_pk_mul_f32 v[42:43], v[42:43], v[6:7] op_sel_hi:[1,0]
	v_pk_mul_f32 v[44:45], v[44:45], v[6:7] op_sel_hi:[1,0]
	v_pk_mul_f32 v[46:47], v[46:47], v[6:7] op_sel_hi:[1,0]
	v_pk_mul_f32 v[32:33], v[32:33], v[112:113]
	v_pk_mul_f32 v[34:35], v[34:35], v[114:115]
	v_pk_mul_f32 v[36:37], v[36:37], v[116:117]
	v_pk_mul_f32 v[38:39], v[38:39], v[118:119]
	v_pk_mul_f32 v[40:41], v[40:41], v[120:121]
	v_pk_mul_f32 v[42:43], v[42:43], v[122:123]
	v_pk_mul_f32 v[44:45], v[44:45], v[124:125]
	v_pk_mul_f32 v[46:47], v[46:47], v[126:127]
	v_pk_fma_f32 v[32:33], v[32:33], v[128:129], v[144:145]
	v_pk_fma_f32 v[34:35], v[34:35], v[130:131], v[146:147]
	v_pk_fma_f32 v[36:37], v[36:37], v[132:133], v[148:149]
	v_pk_fma_f32 v[38:39], v[38:39], v[134:135], v[150:151]
	v_pk_fma_f32 v[40:41], v[40:41], v[136:137], v[152:153]
	v_pk_fma_f32 v[42:43], v[42:43], v[138:139], v[154:155]
	v_pk_fma_f32 v[44:45], v[44:45], v[140:141], v[156:157]
	v_pk_fma_f32 v[46:47], v[46:47], v[142:143], v[158:159]
	v_cvt_pk_bf16_f32 v32, v32, v33
	v_cvt_pk_bf16_f32 v33, v34, v35
	v_cvt_pk_bf16_f32 v34, v36, v37
	v_cvt_pk_bf16_f32 v35, v38, v39
	v_cvt_pk_bf16_f32 v36, v40, v41
	v_cvt_pk_bf16_f32 v37, v42, v43
	v_cvt_pk_bf16_f32 v38, v44, v45
	v_cvt_pk_bf16_f32 v39, v46, v47
	s_lshl_b32 s99, s98, 11
	v_lshl_add_u32 v8, v0, 3, s99
	global_store_dwordx2 v8, v[32:33], s[94:95]
	global_store_dwordx2 v8, v[34:35], s[94:95] offset:512
	global_store_dwordx2 v8, v[36:37], s[94:95] offset:1024
	global_store_dwordx2 v8, v[38:39], s[94:95] offset:1536
	s_lshl_b32 s99, s98, 2
	v_mov_b32_e32 v9, s99
	v_mov_b32_e32 v10, 0
	v_cmp_eq_u32_e32 vcc, 0, v0
	s_and_saveexec_b64 s[98:99], vcc
	global_store_dword v9, v10, s[90:91]
	global_store_dword v9, v10, s[92:93]
	s_or_b64 exec, exec, s[98:99]
	s_add_u32 s98, s97, 13
	s_lshl_b32 s98, s98, 12
	v_add_u32_e32 v3, s98, v1
	global_load_dwordx4 v[32:35], v3, s[88:89] nt
	global_load_dwordx4 v[36:39], v3, s[88:89] offset:1024 nt
	global_load_dwordx4 v[40:43], v3, s[88:89] offset:2048 nt
	global_load_dwordx4 v[44:47], v3, s[88:89] offset:3072 nt
	s_waitcnt vmcnt(50)
	v_mul_f32_e32 v4, v48, v48
	v_fma_f32 v4, v49, v49, v4
	v_fma_f32 v4, v50, v50, v4
	v_fma_f32 v4, v51, v51, v4
	v_fma_f32 v4, v52, v52, v4
	v_fma_f32 v4, v53, v53, v4
	v_fma_f32 v4, v54, v54, v4
	v_fma_f32 v4, v55, v55, v4
	v_fma_f32 v4, v56, v56, v4
	v_fma_f32 v4, v57, v57, v4
	v_fma_f32 v4, v58, v58, v4
	v_fma_f32 v4, v59, v59, v4
	v_fma_f32 v4, v60, v60, v4
	v_fma_f32 v4, v61, v61, v4
	v_fma_f32 v4, v62, v62, v4
	v_fma_f32 v4, v63, v63, v4
	s_nop 1
	v_add_f32_dpp v5, v4, v4 quad_perm:[1,0,3,2] row_mask:0xf bank_mask:0xf
	s_nop 1
	v_add_f32_dpp v4, v5, v5 quad_perm:[2,3,0,1] row_mask:0xf bank_mask:0xf
	s_nop 1
	v_add_f32_dpp v5, v4, v4 row_half_mirror row_mask:0xf bank_mask:0xf
	s_nop 1
	v_add_f32_dpp v4, v5, v5 row_mirror row_mask:0xf bank_mask:0xf
	s_nop 1
	v_readlane_b32 s98, v4, 0
	v_readlane_b32 s99, v4, 16
	s_nop 3
	v_mov_b32_e32 v5, s98
	v_add_f32_e32 v5, s99, v5
	v_readlane_b32 s98, v4, 32
	v_readlane_b32 s99, v4, 48
	s_nop 3
	v_add_f32_e32 v5, s98, v5
	v_add_f32_e32 v5, s99, v5
	v_mul_f32_e32 v5, 0x3a800000, v5
	v_add_f32_e32 v5, 0x358637bd, v5
	v_rsq_f32_e32 v6, v5
	s_nop 0
	s_add_u32 s98, s97, 8
	v_pk_mul_f32 v[48:49], v[48:49], v[6:7] op_sel_hi:[1,0]
	v_pk_mul_f32 v[50:51], v[50:51], v[6:7] op_sel_hi:[1,0]
	v_pk_mul_f32 v[52:53], v[52:53], v[6:7] op_sel_hi:[1,0]
	v_pk_mul_f32 v[54:55], v[54:55], v[6:7] op_sel_hi:[1,0]
	v_pk_mul_f32 v[56:57], v[56:57], v[6:7] op_sel_hi:[1,0]
	v_pk_mul_f32 v[58:59], v[58:59], v[6:7] op_sel_hi:[1,0]
	v_pk_mul_f32 v[60:61], v[60:61], v[6:7] op_sel_hi:[1,0]
	v_pk_mul_f32 v[62:63], v[62:63], v[6:7] op_sel_hi:[1,0]
	v_pk_mul_f32 v[48:49], v[48:49], v[112:113]
	v_pk_mul_f32 v[50:51], v[50:51], v[114:115]
	v_pk_mul_f32 v[52:53], v[52:53], v[116:117]
	v_pk_mul_f32 v[54:55], v[54:55], v[118:119]
	v_pk_mul_f32 v[56:57], v[56:57], v[120:121]
	v_pk_mul_f32 v[58:59], v[58:59], v[122:123]
	v_pk_mul_f32 v[60:61], v[60:61], v[124:125]
	v_pk_mul_f32 v[62:63], v[62:63], v[126:127]
	v_pk_fma_f32 v[48:49], v[48:49], v[128:129], v[144:145]
	v_pk_fma_f32 v[50:51], v[50:51], v[130:131], v[146:147]
	v_pk_fma_f32 v[52:53], v[52:53], v[132:133], v[148:149]
	v_pk_fma_f32 v[54:55], v[54:55], v[134:135], v[150:151]
	v_pk_fma_f32 v[56:57], v[56:57], v[136:137], v[152:153]
	v_pk_fma_f32 v[58:59], v[58:59], v[138:139], v[154:155]
	v_pk_fma_f32 v[60:61], v[60:61], v[140:141], v[156:157]
	v_pk_fma_f32 v[62:63], v[62:63], v[142:143], v[158:159]
	v_cvt_pk_bf16_f32 v48, v48, v49
	v_cvt_pk_bf16_f32 v49, v50, v51
	v_cvt_pk_bf16_f32 v50, v52, v53
	v_cvt_pk_bf16_f32 v51, v54, v55
	v_cvt_pk_bf16_f32 v52, v56, v57
	v_cvt_pk_bf16_f32 v53, v58, v59
	v_cvt_pk_bf16_f32 v54, v60, v61
	v_cvt_pk_bf16_f32 v55, v62, v63
	s_lshl_b32 s99, s98, 11
	v_lshl_add_u32 v8, v0, 3, s99
	global_store_dwordx2 v8, v[48:49], s[94:95]
	global_store_dwordx2 v8, v[50:51], s[94:95] offset:512
	global_store_dwordx2 v8, v[52:53], s[94:95] offset:1024
	global_store_dwordx2 v8, v[54:55], s[94:95] offset:1536
	s_lshl_b32 s99, s98, 2
	v_mov_b32_e32 v9, s99
	v_mov_b32_e32 v10, 0
	v_cmp_eq_u32_e32 vcc, 0, v0
	s_and_saveexec_b64 s[98:99], vcc
	global_store_dword v9, v10, s[90:91]
	global_store_dword v9, v10, s[92:93]
	s_or_b64 exec, exec, s[98:99]
	s_add_u32 s98, s97, 14
	s_lshl_b32 s98, s98, 12
	v_add_u32_e32 v3, s98, v1
	global_load_dwordx4 v[48:51], v3, s[88:89] nt
	global_load_dwordx4 v[52:55], v3, s[88:89] offset:1024 nt
	global_load_dwordx4 v[56:59], v3, s[88:89] offset:2048 nt
	global_load_dwordx4 v[60:63], v3, s[88:89] offset:3072 nt
	s_waitcnt vmcnt(50)
	v_mul_f32_e32 v4, v64, v64
	v_fma_f32 v4, v65, v65, v4
	v_fma_f32 v4, v66, v66, v4
	v_fma_f32 v4, v67, v67, v4
	v_fma_f32 v4, v68, v68, v4
	v_fma_f32 v4, v69, v69, v4
	v_fma_f32 v4, v70, v70, v4
	v_fma_f32 v4, v71, v71, v4
	v_fma_f32 v4, v72, v72, v4
	v_fma_f32 v4, v73, v73, v4
	v_fma_f32 v4, v74, v74, v4
	v_fma_f32 v4, v75, v75, v4
	v_fma_f32 v4, v76, v76, v4
	v_fma_f32 v4, v77, v77, v4
	v_fma_f32 v4, v78, v78, v4
	v_fma_f32 v4, v79, v79, v4
	s_nop 1
	v_add_f32_dpp v5, v4, v4 quad_perm:[1,0,3,2] row_mask:0xf bank_mask:0xf
	s_nop 1
	v_add_f32_dpp v4, v5, v5 quad_perm:[2,3,0,1] row_mask:0xf bank_mask:0xf
	s_nop 1
	v_add_f32_dpp v5, v4, v4 row_half_mirror row_mask:0xf bank_mask:0xf
	s_nop 1
	v_add_f32_dpp v4, v5, v5 row_mirror row_mask:0xf bank_mask:0xf
	s_nop 1
	v_readlane_b32 s98, v4, 0
	v_readlane_b32 s99, v4, 16
	s_nop 3
	v_mov_b32_e32 v5, s98
	v_add_f32_e32 v5, s99, v5
	v_readlane_b32 s98, v4, 32
	v_readlane_b32 s99, v4, 48
	s_nop 3
	v_add_f32_e32 v5, s98, v5
	v_add_f32_e32 v5, s99, v5
	v_mul_f32_e32 v5, 0x3a800000, v5
	v_add_f32_e32 v5, 0x358637bd, v5
	v_rsq_f32_e32 v6, v5
	s_nop 0
	s_add_u32 s98, s97, 9
	v_pk_mul_f32 v[64:65], v[64:65], v[6:7] op_sel_hi:[1,0]
	v_pk_mul_f32 v[66:67], v[66:67], v[6:7] op_sel_hi:[1,0]
	v_pk_mul_f32 v[68:69], v[68:69], v[6:7] op_sel_hi:[1,0]
	v_pk_mul_f32 v[70:71], v[70:71], v[6:7] op_sel_hi:[1,0]
	v_pk_mul_f32 v[72:73], v[72:73], v[6:7] op_sel_hi:[1,0]
	v_pk_mul_f32 v[74:75], v[74:75], v[6:7] op_sel_hi:[1,0]
	v_pk_mul_f32 v[76:77], v[76:77], v[6:7] op_sel_hi:[1,0]
	v_pk_mul_f32 v[78:79], v[78:79], v[6:7] op_sel_hi:[1,0]
	v_pk_mul_f32 v[64:65], v[64:65], v[112:113]
	v_pk_mul_f32 v[66:67], v[66:67], v[114:115]
	v_pk_mul_f32 v[68:69], v[68:69], v[116:117]
	v_pk_mul_f32 v[70:71], v[70:71], v[118:119]
	v_pk_mul_f32 v[72:73], v[72:73], v[120:121]
	v_pk_mul_f32 v[74:75], v[74:75], v[122:123]
	v_pk_mul_f32 v[76:77], v[76:77], v[124:125]
	v_pk_mul_f32 v[78:79], v[78:79], v[126:127]
	v_pk_fma_f32 v[64:65], v[64:65], v[128:129], v[144:145]
	v_pk_fma_f32 v[66:67], v[66:67], v[130:131], v[146:147]
	v_pk_fma_f32 v[68:69], v[68:69], v[132:133], v[148:149]
	v_pk_fma_f32 v[70:71], v[70:71], v[134:135], v[150:151]
	v_pk_fma_f32 v[72:73], v[72:73], v[136:137], v[152:153]
	v_pk_fma_f32 v[74:75], v[74:75], v[138:139], v[154:155]
	v_pk_fma_f32 v[76:77], v[76:77], v[140:141], v[156:157]
	v_pk_fma_f32 v[78:79], v[78:79], v[142:143], v[158:159]
	v_cvt_pk_bf16_f32 v64, v64, v65
	v_cvt_pk_bf16_f32 v65, v66, v67
	v_cvt_pk_bf16_f32 v66, v68, v69
	v_cvt_pk_bf16_f32 v67, v70, v71
	v_cvt_pk_bf16_f32 v68, v72, v73
	v_cvt_pk_bf16_f32 v69, v74, v75
	v_cvt_pk_bf16_f32 v70, v76, v77
	v_cvt_pk_bf16_f32 v71, v78, v79
	s_lshl_b32 s99, s98, 11
	v_lshl_add_u32 v8, v0, 3, s99
	global_store_dwordx2 v8, v[64:65], s[94:95]
	global_store_dwordx2 v8, v[66:67], s[94:95] offset:512
	global_store_dwordx2 v8, v[68:69], s[94:95] offset:1024
	global_store_dwordx2 v8, v[70:71], s[94:95] offset:1536
	s_lshl_b32 s99, s98, 2
	v_mov_b32_e32 v9, s99
	v_mov_b32_e32 v10, 0
	v_cmp_eq_u32_e32 vcc, 0, v0
	s_and_saveexec_b64 s[98:99], vcc
	global_store_dword v9, v10, s[90:91]
	global_store_dword v9, v10, s[92:93]
	s_or_b64 exec, exec, s[98:99]
	s_add_u32 s98, s97, 15
	s_lshl_b32 s98, s98, 12
	v_add_u32_e32 v3, s98, v1
	global_load_dwordx4 v[64:67], v3, s[88:89] nt
	global_load_dwordx4 v[68:71], v3, s[88:89] offset:1024 nt
	global_load_dwordx4 v[72:75], v3, s[88:89] offset:2048 nt
	global_load_dwordx4 v[76:79], v3, s[88:89] offset:3072 nt
	s_waitcnt vmcnt(50)
	v_mul_f32_e32 v4, v80, v80
	v_fma_f32 v4, v81, v81, v4
	v_fma_f32 v4, v82, v82, v4
	v_fma_f32 v4, v83, v83, v4
	v_fma_f32 v4, v84, v84, v4
	v_fma_f32 v4, v85, v85, v4
	v_fma_f32 v4, v86, v86, v4
	v_fma_f32 v4, v87, v87, v4
	v_fma_f32 v4, v88, v88, v4
	v_fma_f32 v4, v89, v89, v4
	v_fma_f32 v4, v90, v90, v4
	v_fma_f32 v4, v91, v91, v4
	v_fma_f32 v4, v92, v92, v4
	v_fma_f32 v4, v93, v93, v4
	v_fma_f32 v4, v94, v94, v4
	v_fma_f32 v4, v95, v95, v4
	s_nop 1
	v_add_f32_dpp v5, v4, v4 quad_perm:[1,0,3,2] row_mask:0xf bank_mask:0xf
	s_nop 1
	v_add_f32_dpp v4, v5, v5 quad_perm:[2,3,0,1] row_mask:0xf bank_mask:0xf
	s_nop 1
	v_add_f32_dpp v5, v4, v4 row_half_mirror row_mask:0xf bank_mask:0xf
	s_nop 1
	v_add_f32_dpp v4, v5, v5 row_mirror row_mask:0xf bank_mask:0xf
	s_nop 1
	v_readlane_b32 s98, v4, 0
	v_readlane_b32 s99, v4, 16
	s_nop 3
	v_mov_b32_e32 v5, s98
	v_add_f32_e32 v5, s99, v5
	v_readlane_b32 s98, v4, 32
	v_readlane_b32 s99, v4, 48
	s_nop 3
	v_add_f32_e32 v5, s98, v5
	v_add_f32_e32 v5, s99, v5
	v_mul_f32_e32 v5, 0x3a800000, v5
	v_add_f32_e32 v5, 0x358637bd, v5
	v_rsq_f32_e32 v6, v5
	s_nop 0
	s_add_u32 s98, s97, 10
	v_pk_mul_f32 v[80:81], v[80:81], v[6:7] op_sel_hi:[1,0]
	v_pk_mul_f32 v[82:83], v[82:83], v[6:7] op_sel_hi:[1,0]
	v_pk_mul_f32 v[84:85], v[84:85], v[6:7] op_sel_hi:[1,0]
	v_pk_mul_f32 v[86:87], v[86:87], v[6:7] op_sel_hi:[1,0]
	v_pk_mul_f32 v[88:89], v[88:89], v[6:7] op_sel_hi:[1,0]
	v_pk_mul_f32 v[90:91], v[90:91], v[6:7] op_sel_hi:[1,0]
	v_pk_mul_f32 v[92:93], v[92:93], v[6:7] op_sel_hi:[1,0]
	v_pk_mul_f32 v[94:95], v[94:95], v[6:7] op_sel_hi:[1,0]
	v_pk_mul_f32 v[80:81], v[80:81], v[112:113]
	v_pk_mul_f32 v[82:83], v[82:83], v[114:115]
	v_pk_mul_f32 v[84:85], v[84:85], v[116:117]
	v_pk_mul_f32 v[86:87], v[86:87], v[118:119]
	v_pk_mul_f32 v[88:89], v[88:89], v[120:121]
	v_pk_mul_f32 v[90:91], v[90:91], v[122:123]
	v_pk_mul_f32 v[92:93], v[92:93], v[124:125]
	v_pk_mul_f32 v[94:95], v[94:95], v[126:127]
	v_pk_fma_f32 v[80:81], v[80:81], v[128:129], v[144:145]
	v_pk_fma_f32 v[82:83], v[82:83], v[130:131], v[146:147]
	v_pk_fma_f32 v[84:85], v[84:85], v[132:133], v[148:149]
	v_pk_fma_f32 v[86:87], v[86:87], v[134:135], v[150:151]
	v_pk_fma_f32 v[88:89], v[88:89], v[136:137], v[152:153]
	v_pk_fma_f32 v[90:91], v[90:91], v[138:139], v[154:155]
	v_pk_fma_f32 v[92:93], v[92:93], v[140:141], v[156:157]
	v_pk_fma_f32 v[94:95], v[94:95], v[142:143], v[158:159]
	v_cvt_pk_bf16_f32 v80, v80, v81
	v_cvt_pk_bf16_f32 v81, v82, v83
	v_cvt_pk_bf16_f32 v82, v84, v85
	v_cvt_pk_bf16_f32 v83, v86, v87
	v_cvt_pk_bf16_f32 v84, v88, v89
	v_cvt_pk_bf16_f32 v85, v90, v91
	v_cvt_pk_bf16_f32 v86, v92, v93
	v_cvt_pk_bf16_f32 v87, v94, v95
	s_lshl_b32 s99, s98, 11
	v_lshl_add_u32 v8, v0, 3, s99
	global_store_dwordx2 v8, v[80:81], s[94:95]
	global_store_dwordx2 v8, v[82:83], s[94:95] offset:512
	global_store_dwordx2 v8, v[84:85], s[94:95] offset:1024
	global_store_dwordx2 v8, v[86:87], s[94:95] offset:1536
	s_lshl_b32 s99, s98, 2
	v_mov_b32_e32 v9, s99
	v_mov_b32_e32 v10, 0
	v_cmp_eq_u32_e32 vcc, 0, v0
	s_and_saveexec_b64 s[98:99], vcc
	global_store_dword v9, v10, s[90:91]
	global_store_dword v9, v10, s[92:93]
	s_or_b64 exec, exec, s[98:99]
	s_waitcnt vmcnt(46)
	v_mul_f32_e32 v4, v96, v96
	v_fma_f32 v4, v97, v97, v4
	v_fma_f32 v4, v98, v98, v4
	v_fma_f32 v4, v99, v99, v4
	v_fma_f32 v4, v100, v100, v4
	v_fma_f32 v4, v101, v101, v4
	v_fma_f32 v4, v102, v102, v4
	v_fma_f32 v4, v103, v103, v4
	v_fma_f32 v4, v104, v104, v4
	v_fma_f32 v4, v105, v105, v4
	v_fma_f32 v4, v106, v106, v4
	v_fma_f32 v4, v107, v107, v4
	v_fma_f32 v4, v108, v108, v4
	v_fma_f32 v4, v109, v109, v4
	v_fma_f32 v4, v110, v110, v4
	v_fma_f32 v4, v111, v111, v4
	s_nop 1
	v_add_f32_dpp v5, v4, v4 quad_perm:[1,0,3,2] row_mask:0xf bank_mask:0xf
	s_nop 1
	v_add_f32_dpp v4, v5, v5 quad_perm:[2,3,0,1] row_mask:0xf bank_mask:0xf
	s_nop 1
	v_add_f32_dpp v5, v4, v4 row_half_mirror row_mask:0xf bank_mask:0xf
	s_nop 1
	v_add_f32_dpp v4, v5, v5 row_mirror row_mask:0xf bank_mask:0xf
	s_nop 1
	v_readlane_b32 s98, v4, 0
	v_readlane_b32 s99, v4, 16
	s_nop 3
	v_mov_b32_e32 v5, s98
	v_add_f32_e32 v5, s99, v5
	v_readlane_b32 s98, v4, 32
	v_readlane_b32 s99, v4, 48
	s_nop 3
	v_add_f32_e32 v5, s98, v5
	v_add_f32_e32 v5, s99, v5
	v_mul_f32_e32 v5, 0x3a800000, v5
	v_add_f32_e32 v5, 0x358637bd, v5
	v_rsq_f32_e32 v6, v5
	s_nop 0
	s_add_u32 s98, s97, 11
	v_pk_mul_f32 v[96:97], v[96:97], v[6:7] op_sel_hi:[1,0]
	v_pk_mul_f32 v[98:99], v[98:99], v[6:7] op_sel_hi:[1,0]
	v_pk_mul_f32 v[100:101], v[100:101], v[6:7] op_sel_hi:[1,0]
	v_pk_mul_f32 v[102:103], v[102:103], v[6:7] op_sel_hi:[1,0]
	v_pk_mul_f32 v[104:105], v[104:105], v[6:7] op_sel_hi:[1,0]
	v_pk_mul_f32 v[106:107], v[106:107], v[6:7] op_sel_hi:[1,0]
	v_pk_mul_f32 v[108:109], v[108:109], v[6:7] op_sel_hi:[1,0]
	v_pk_mul_f32 v[110:111], v[110:111], v[6:7] op_sel_hi:[1,0]
	v_pk_mul_f32 v[96:97], v[96:97], v[112:113]
	v_pk_mul_f32 v[98:99], v[98:99], v[114:115]
	v_pk_mul_f32 v[100:101], v[100:101], v[116:117]
	v_pk_mul_f32 v[102:103], v[102:103], v[118:119]
	v_pk_mul_f32 v[104:105], v[104:105], v[120:121]
	v_pk_mul_f32 v[106:107], v[106:107], v[122:123]
	v_pk_mul_f32 v[108:109], v[108:109], v[124:125]
	v_pk_mul_f32 v[110:111], v[110:111], v[126:127]
	v_pk_fma_f32 v[96:97], v[96:97], v[128:129], v[144:145]
	v_pk_fma_f32 v[98:99], v[98:99], v[130:131], v[146:147]
	v_pk_fma_f32 v[100:101], v[100:101], v[132:133], v[148:149]
	v_pk_fma_f32 v[102:103], v[102:103], v[134:135], v[150:151]
	v_pk_fma_f32 v[104:105], v[104:105], v[136:137], v[152:153]
	v_pk_fma_f32 v[106:107], v[106:107], v[138:139], v[154:155]
	v_pk_fma_f32 v[108:109], v[108:109], v[140:141], v[156:157]
	v_pk_fma_f32 v[110:111], v[110:111], v[142:143], v[158:159]
	v_cvt_pk_bf16_f32 v96, v96, v97
	v_cvt_pk_bf16_f32 v97, v98, v99
	v_cvt_pk_bf16_f32 v98, v100, v101
	v_cvt_pk_bf16_f32 v99, v102, v103
	v_cvt_pk_bf16_f32 v100, v104, v105
	v_cvt_pk_bf16_f32 v101, v106, v107
	v_cvt_pk_bf16_f32 v102, v108, v109
	v_cvt_pk_bf16_f32 v103, v110, v111
	s_lshl_b32 s99, s98, 11
	v_lshl_add_u32 v8, v0, 3, s99
	global_store_dwordx2 v8, v[96:97], s[94:95]
	global_store_dwordx2 v8, v[98:99], s[94:95] offset:512
	global_store_dwordx2 v8, v[100:101], s[94:95] offset:1024
	global_store_dwordx2 v8, v[102:103], s[94:95] offset:1536
	s_lshl_b32 s99, s98, 2
	v_mov_b32_e32 v9, s99
	v_mov_b32_e32 v10, 0
	v_cmp_eq_u32_e32 vcc, 0, v0
	s_and_saveexec_b64 s[98:99], vcc
	global_store_dword v9, v10, s[90:91]
	global_store_dword v9, v10, s[92:93]
	s_or_b64 exec, exec, s[98:99]
	s_waitcnt vmcnt(42)
	v_mul_f32_e32 v4, v16, v16
	v_fma_f32 v4, v17, v17, v4
	v_fma_f32 v4, v18, v18, v4
	v_fma_f32 v4, v19, v19, v4
	v_fma_f32 v4, v20, v20, v4
	v_fma_f32 v4, v21, v21, v4
	v_fma_f32 v4, v22, v22, v4
	v_fma_f32 v4, v23, v23, v4
	v_fma_f32 v4, v24, v24, v4
	v_fma_f32 v4, v25, v25, v4
	v_fma_f32 v4, v26, v26, v4
	v_fma_f32 v4, v27, v27, v4
	v_fma_f32 v4, v28, v28, v4
	v_fma_f32 v4, v29, v29, v4
	v_fma_f32 v4, v30, v30, v4
	v_fma_f32 v4, v31, v31, v4
	s_nop 1
	v_add_f32_dpp v5, v4, v4 quad_perm:[1,0,3,2] row_mask:0xf bank_mask:0xf
	s_nop 1
	v_add_f32_dpp v4, v5, v5 quad_perm:[2,3,0,1] row_mask:0xf bank_mask:0xf
	s_nop 1
	v_add_f32_dpp v5, v4, v4 row_half_mirror row_mask:0xf bank_mask:0xf
	s_nop 1
	v_add_f32_dpp v4, v5, v5 row_mirror row_mask:0xf bank_mask:0xf
	s_nop 1
	v_readlane_b32 s98, v4, 0
	v_readlane_b32 s99, v4, 16
	s_nop 3
	v_mov_b32_e32 v5, s98
	v_add_f32_e32 v5, s99, v5
	v_readlane_b32 s98, v4, 32
	v_readlane_b32 s99, v4, 48
	s_nop 3
	v_add_f32_e32 v5, s98, v5
	v_add_f32_e32 v5, s99, v5
	v_mul_f32_e32 v5, 0x3a800000, v5
	v_add_f32_e32 v5, 0x358637bd, v5
	v_rsq_f32_e32 v6, v5
	s_nop 0
	s_add_u32 s98, s97, 12
	v_pk_mul_f32 v[16:17], v[16:17], v[6:7] op_sel_hi:[1,0]
	v_pk_mul_f32 v[18:19], v[18:19], v[6:7] op_sel_hi:[1,0]
	v_pk_mul_f32 v[20:21], v[20:21], v[6:7] op_sel_hi:[1,0]
	v_pk_mul_f32 v[22:23], v[22:23], v[6:7] op_sel_hi:[1,0]
	v_pk_mul_f32 v[24:25], v[24:25], v[6:7] op_sel_hi:[1,0]
	v_pk_mul_f32 v[26:27], v[26:27], v[6:7] op_sel_hi:[1,0]
	v_pk_mul_f32 v[28:29], v[28:29], v[6:7] op_sel_hi:[1,0]
	v_pk_mul_f32 v[30:31], v[30:31], v[6:7] op_sel_hi:[1,0]
	v_pk_mul_f32 v[16:17], v[16:17], v[112:113]
	v_pk_mul_f32 v[18:19], v[18:19], v[114:115]
	v_pk_mul_f32 v[20:21], v[20:21], v[116:117]
	v_pk_mul_f32 v[22:23], v[22:23], v[118:119]
	v_pk_mul_f32 v[24:25], v[24:25], v[120:121]
	v_pk_mul_f32 v[26:27], v[26:27], v[122:123]
	v_pk_mul_f32 v[28:29], v[28:29], v[124:125]
	v_pk_mul_f32 v[30:31], v[30:31], v[126:127]
	v_pk_fma_f32 v[16:17], v[16:17], v[128:129], v[144:145]
	v_pk_fma_f32 v[18:19], v[18:19], v[130:131], v[146:147]
	v_pk_fma_f32 v[20:21], v[20:21], v[132:133], v[148:149]
	v_pk_fma_f32 v[22:23], v[22:23], v[134:135], v[150:151]
	v_pk_fma_f32 v[24:25], v[24:25], v[136:137], v[152:153]
	v_pk_fma_f32 v[26:27], v[26:27], v[138:139], v[154:155]
	v_pk_fma_f32 v[28:29], v[28:29], v[140:141], v[156:157]
	v_pk_fma_f32 v[30:31], v[30:31], v[142:143], v[158:159]
	v_cvt_pk_bf16_f32 v16, v16, v17
	v_cvt_pk_bf16_f32 v17, v18, v19
	v_cvt_pk_bf16_f32 v18, v20, v21
	v_cvt_pk_bf16_f32 v19, v22, v23
	v_cvt_pk_bf16_f32 v20, v24, v25
	v_cvt_pk_bf16_f32 v21, v26, v27
	v_cvt_pk_bf16_f32 v22, v28, v29
	v_cvt_pk_bf16_f32 v23, v30, v31
	s_lshl_b32 s99, s98, 11
	v_lshl_add_u32 v8, v0, 3, s99
	global_store_dwordx2 v8, v[16:17], s[94:95]
	global_store_dwordx2 v8, v[18:19], s[94:95] offset:512
	global_store_dwordx2 v8, v[20:21], s[94:95] offset:1024
	global_store_dwordx2 v8, v[22:23], s[94:95] offset:1536
	s_lshl_b32 s99, s98, 2
	v_mov_b32_e32 v9, s99
	v_mov_b32_e32 v10, 0
	v_cmp_eq_u32_e32 vcc, 0, v0
	s_and_saveexec_b64 s[98:99], vcc
	global_store_dword v9, v10, s[90:91]
	global_store_dword v9, v10, s[92:93]
	s_or_b64 exec, exec, s[98:99]
	s_waitcnt vmcnt(38)
	v_mul_f32_e32 v4, v32, v32
	v_fma_f32 v4, v33, v33, v4
	v_fma_f32 v4, v34, v34, v4
	v_fma_f32 v4, v35, v35, v4
	v_fma_f32 v4, v36, v36, v4
	v_fma_f32 v4, v37, v37, v4
	v_fma_f32 v4, v38, v38, v4
	v_fma_f32 v4, v39, v39, v4
	v_fma_f32 v4, v40, v40, v4
	v_fma_f32 v4, v41, v41, v4
	v_fma_f32 v4, v42, v42, v4
	v_fma_f32 v4, v43, v43, v4
	v_fma_f32 v4, v44, v44, v4
	v_fma_f32 v4, v45, v45, v4
	v_fma_f32 v4, v46, v46, v4
	v_fma_f32 v4, v47, v47, v4
	s_nop 1
	v_add_f32_dpp v5, v4, v4 quad_perm:[1,0,3,2] row_mask:0xf bank_mask:0xf
	s_nop 1
	v_add_f32_dpp v4, v5, v5 quad_perm:[2,3,0,1] row_mask:0xf bank_mask:0xf
	s_nop 1
	v_add_f32_dpp v5, v4, v4 row_half_mirror row_mask:0xf bank_mask:0xf
	s_nop 1
	v_add_f32_dpp v4, v5, v5 row_mirror row_mask:0xf bank_mask:0xf
	s_nop 1
	v_readlane_b32 s98, v4, 0
	v_readlane_b32 s99, v4, 16
	s_nop 3
	v_mov_b32_e32 v5, s98
	v_add_f32_e32 v5, s99, v5
	v_readlane_b32 s98, v4, 32
	v_readlane_b32 s99, v4, 48
	s_nop 3
	v_add_f32_e32 v5, s98, v5
	v_add_f32_e32 v5, s99, v5
	v_mul_f32_e32 v5, 0x3a800000, v5
	v_add_f32_e32 v5, 0x358637bd, v5
	v_rsq_f32_e32 v6, v5
	s_nop 0
	s_add_u32 s98, s97, 13
	v_pk_mul_f32 v[32:33], v[32:33], v[6:7] op_sel_hi:[1,0]
	v_pk_mul_f32 v[34:35], v[34:35], v[6:7] op_sel_hi:[1,0]
	v_pk_mul_f32 v[36:37], v[36:37], v[6:7] op_sel_hi:[1,0]
	v_pk_mul_f32 v[38:39], v[38:39], v[6:7] op_sel_hi:[1,0]
	v_pk_mul_f32 v[40:41], v[40:41], v[6:7] op_sel_hi:[1,0]
	v_pk_mul_f32 v[42:43], v[42:43], v[6:7] op_sel_hi:[1,0]
	v_pk_mul_f32 v[44:45], v[44:45], v[6:7] op_sel_hi:[1,0]
	v_pk_mul_f32 v[46:47], v[46:47], v[6:7] op_sel_hi:[1,0]
	v_pk_mul_f32 v[32:33], v[32:33], v[112:113]
	v_pk_mul_f32 v[34:35], v[34:35], v[114:115]
	v_pk_mul_f32 v[36:37], v[36:37], v[116:117]
	v_pk_mul_f32 v[38:39], v[38:39], v[118:119]
	v_pk_mul_f32 v[40:41], v[40:41], v[120:121]
	v_pk_mul_f32 v[42:43], v[42:43], v[122:123]
	v_pk_mul_f32 v[44:45], v[44:45], v[124:125]
	v_pk_mul_f32 v[46:47], v[46:47], v[126:127]
	v_pk_fma_f32 v[32:33], v[32:33], v[128:129], v[144:145]
	v_pk_fma_f32 v[34:35], v[34:35], v[130:131], v[146:147]
	v_pk_fma_f32 v[36:37], v[36:37], v[132:133], v[148:149]
	v_pk_fma_f32 v[38:39], v[38:39], v[134:135], v[150:151]
	v_pk_fma_f32 v[40:41], v[40:41], v[136:137], v[152:153]
	v_pk_fma_f32 v[42:43], v[42:43], v[138:139], v[154:155]
	v_pk_fma_f32 v[44:45], v[44:45], v[140:141], v[156:157]
	v_pk_fma_f32 v[46:47], v[46:47], v[142:143], v[158:159]
	v_cvt_pk_bf16_f32 v32, v32, v33
	v_cvt_pk_bf16_f32 v33, v34, v35
	v_cvt_pk_bf16_f32 v34, v36, v37
	v_cvt_pk_bf16_f32 v35, v38, v39
	v_cvt_pk_bf16_f32 v36, v40, v41
	v_cvt_pk_bf16_f32 v37, v42, v43
	v_cvt_pk_bf16_f32 v38, v44, v45
	v_cvt_pk_bf16_f32 v39, v46, v47
	s_lshl_b32 s99, s98, 11
	v_lshl_add_u32 v8, v0, 3, s99
	global_store_dwordx2 v8, v[32:33], s[94:95]
	global_store_dwordx2 v8, v[34:35], s[94:95] offset:512
	global_store_dwordx2 v8, v[36:37], s[94:95] offset:1024
	global_store_dwordx2 v8, v[38:39], s[94:95] offset:1536
	s_lshl_b32 s99, s98, 2
	v_mov_b32_e32 v9, s99
	v_mov_b32_e32 v10, 0
	v_cmp_eq_u32_e32 vcc, 0, v0
	s_and_saveexec_b64 s[98:99], vcc
	global_store_dword v9, v10, s[90:91]
	global_store_dword v9, v10, s[92:93]
	s_or_b64 exec, exec, s[98:99]
	s_waitcnt vmcnt(34)
	v_mul_f32_e32 v4, v48, v48
	v_fma_f32 v4, v49, v49, v4
	v_fma_f32 v4, v50, v50, v4
	v_fma_f32 v4, v51, v51, v4
	v_fma_f32 v4, v52, v52, v4
	v_fma_f32 v4, v53, v53, v4
	v_fma_f32 v4, v54, v54, v4
	v_fma_f32 v4, v55, v55, v4
	v_fma_f32 v4, v56, v56, v4
	v_fma_f32 v4, v57, v57, v4
	v_fma_f32 v4, v58, v58, v4
	v_fma_f32 v4, v59, v59, v4
	v_fma_f32 v4, v60, v60, v4
	v_fma_f32 v4, v61, v61, v4
	v_fma_f32 v4, v62, v62, v4
	v_fma_f32 v4, v63, v63, v4
	s_nop 1
	v_add_f32_dpp v5, v4, v4 quad_perm:[1,0,3,2] row_mask:0xf bank_mask:0xf
	s_nop 1
	v_add_f32_dpp v4, v5, v5 quad_perm:[2,3,0,1] row_mask:0xf bank_mask:0xf
	s_nop 1
	v_add_f32_dpp v5, v4, v4 row_half_mirror row_mask:0xf bank_mask:0xf
	s_nop 1
	v_add_f32_dpp v4, v5, v5 row_mirror row_mask:0xf bank_mask:0xf
	s_nop 1
	v_readlane_b32 s98, v4, 0
	v_readlane_b32 s99, v4, 16
	s_nop 3
	v_mov_b32_e32 v5, s98
	v_add_f32_e32 v5, s99, v5
	v_readlane_b32 s98, v4, 32
	v_readlane_b32 s99, v4, 48
	s_nop 3
	v_add_f32_e32 v5, s98, v5
	v_add_f32_e32 v5, s99, v5
	v_mul_f32_e32 v5, 0x3a800000, v5
	v_add_f32_e32 v5, 0x358637bd, v5
	v_rsq_f32_e32 v6, v5
	s_nop 0
	s_add_u32 s98, s97, 14
	v_pk_mul_f32 v[48:49], v[48:49], v[6:7] op_sel_hi:[1,0]
	v_pk_mul_f32 v[50:51], v[50:51], v[6:7] op_sel_hi:[1,0]
	v_pk_mul_f32 v[52:53], v[52:53], v[6:7] op_sel_hi:[1,0]
	v_pk_mul_f32 v[54:55], v[54:55], v[6:7] op_sel_hi:[1,0]
	v_pk_mul_f32 v[56:57], v[56:57], v[6:7] op_sel_hi:[1,0]
	v_pk_mul_f32 v[58:59], v[58:59], v[6:7] op_sel_hi:[1,0]
	v_pk_mul_f32 v[60:61], v[60:61], v[6:7] op_sel_hi:[1,0]
	v_pk_mul_f32 v[62:63], v[62:63], v[6:7] op_sel_hi:[1,0]
	v_pk_mul_f32 v[48:49], v[48:49], v[112:113]
	v_pk_mul_f32 v[50:51], v[50:51], v[114:115]
	v_pk_mul_f32 v[52:53], v[52:53], v[116:117]
	v_pk_mul_f32 v[54:55], v[54:55], v[118:119]
	v_pk_mul_f32 v[56:57], v[56:57], v[120:121]
	v_pk_mul_f32 v[58:59], v[58:59], v[122:123]
	v_pk_mul_f32 v[60:61], v[60:61], v[124:125]
	v_pk_mul_f32 v[62:63], v[62:63], v[126:127]
	v_pk_fma_f32 v[48:49], v[48:49], v[128:129], v[144:145]
	v_pk_fma_f32 v[50:51], v[50:51], v[130:131], v[146:147]
	v_pk_fma_f32 v[52:53], v[52:53], v[132:133], v[148:149]
	v_pk_fma_f32 v[54:55], v[54:55], v[134:135], v[150:151]
	v_pk_fma_f32 v[56:57], v[56:57], v[136:137], v[152:153]
	v_pk_fma_f32 v[58:59], v[58:59], v[138:139], v[154:155]
	v_pk_fma_f32 v[60:61], v[60:61], v[140:141], v[156:157]
	v_pk_fma_f32 v[62:63], v[62:63], v[142:143], v[158:159]
	v_cvt_pk_bf16_f32 v48, v48, v49
	v_cvt_pk_bf16_f32 v49, v50, v51
	v_cvt_pk_bf16_f32 v50, v52, v53
	v_cvt_pk_bf16_f32 v51, v54, v55
	v_cvt_pk_bf16_f32 v52, v56, v57
	v_cvt_pk_bf16_f32 v53, v58, v59
	v_cvt_pk_bf16_f32 v54, v60, v61
	v_cvt_pk_bf16_f32 v55, v62, v63
	s_lshl_b32 s99, s98, 11
	v_lshl_add_u32 v8, v0, 3, s99
	global_store_dwordx2 v8, v[48:49], s[94:95]
	global_store_dwordx2 v8, v[50:51], s[94:95] offset:512
	global_store_dwordx2 v8, v[52:53], s[94:95] offset:1024
	global_store_dwordx2 v8, v[54:55], s[94:95] offset:1536
	s_lshl_b32 s99, s98, 2
	v_mov_b32_e32 v9, s99
	v_mov_b32_e32 v10, 0
	v_cmp_eq_u32_e32 vcc, 0, v0
	s_and_saveexec_b64 s[98:99], vcc
	global_store_dword v9, v10, s[90:91]
	global_store_dword v9, v10, s[92:93]
	s_or_b64 exec, exec, s[98:99]
	s_waitcnt vmcnt(30)
	v_mul_f32_e32 v4, v64, v64
	v_fma_f32 v4, v65, v65, v4
	v_fma_f32 v4, v66, v66, v4
	v_fma_f32 v4, v67, v67, v4
	v_fma_f32 v4, v68, v68, v4
	v_fma_f32 v4, v69, v69, v4
	v_fma_f32 v4, v70, v70, v4
	v_fma_f32 v4, v71, v71, v4
	v_fma_f32 v4, v72, v72, v4
	v_fma_f32 v4, v73, v73, v4
	v_fma_f32 v4, v74, v74, v4
	v_fma_f32 v4, v75, v75, v4
	v_fma_f32 v4, v76, v76, v4
	v_fma_f32 v4, v77, v77, v4
	v_fma_f32 v4, v78, v78, v4
	v_fma_f32 v4, v79, v79, v4
	s_nop 1
	v_add_f32_dpp v5, v4, v4 quad_perm:[1,0,3,2] row_mask:0xf bank_mask:0xf
	s_nop 1
	v_add_f32_dpp v4, v5, v5 quad_perm:[2,3,0,1] row_mask:0xf bank_mask:0xf
	s_nop 1
	v_add_f32_dpp v5, v4, v4 row_half_mirror row_mask:0xf bank_mask:0xf
	s_nop 1
	v_add_f32_dpp v4, v5, v5 row_mirror row_mask:0xf bank_mask:0xf
	s_nop 1
	v_readlane_b32 s98, v4, 0
	v_readlane_b32 s99, v4, 16
	s_nop 3
	v_mov_b32_e32 v5, s98
	v_add_f32_e32 v5, s99, v5
	v_readlane_b32 s98, v4, 32
	v_readlane_b32 s99, v4, 48
	s_nop 3
	v_add_f32_e32 v5, s98, v5
	v_add_f32_e32 v5, s99, v5
	v_mul_f32_e32 v5, 0x3a800000, v5
	v_add_f32_e32 v5, 0x358637bd, v5
	v_rsq_f32_e32 v6, v5
	s_nop 0
	s_add_u32 s98, s97, 15
	v_pk_mul_f32 v[64:65], v[64:65], v[6:7] op_sel_hi:[1,0]
	v_pk_mul_f32 v[66:67], v[66:67], v[6:7] op_sel_hi:[1,0]
	v_pk_mul_f32 v[68:69], v[68:69], v[6:7] op_sel_hi:[1,0]
	v_pk_mul_f32 v[70:71], v[70:71], v[6:7] op_sel_hi:[1,0]
	v_pk_mul_f32 v[72:73], v[72:73], v[6:7] op_sel_hi:[1,0]
	v_pk_mul_f32 v[74:75], v[74:75], v[6:7] op_sel_hi:[1,0]
	v_pk_mul_f32 v[76:77], v[76:77], v[6:7] op_sel_hi:[1,0]
	v_pk_mul_f32 v[78:79], v[78:79], v[6:7] op_sel_hi:[1,0]
	v_pk_mul_f32 v[64:65], v[64:65], v[112:113]
	v_pk_mul_f32 v[66:67], v[66:67], v[114:115]
	v_pk_mul_f32 v[68:69], v[68:69], v[116:117]
	v_pk_mul_f32 v[70:71], v[70:71], v[118:119]
	v_pk_mul_f32 v[72:73], v[72:73], v[120:121]
	v_pk_mul_f32 v[74:75], v[74:75], v[122:123]
	v_pk_mul_f32 v[76:77], v[76:77], v[124:125]
	v_pk_mul_f32 v[78:79], v[78:79], v[126:127]
	v_pk_fma_f32 v[64:65], v[64:65], v[128:129], v[144:145]
	v_pk_fma_f32 v[66:67], v[66:67], v[130:131], v[146:147]
	v_pk_fma_f32 v[68:69], v[68:69], v[132:133], v[148:149]
	v_pk_fma_f32 v[70:71], v[70:71], v[134:135], v[150:151]
	v_pk_fma_f32 v[72:73], v[72:73], v[136:137], v[152:153]
	v_pk_fma_f32 v[74:75], v[74:75], v[138:139], v[154:155]
	v_pk_fma_f32 v[76:77], v[76:77], v[140:141], v[156:157]
	v_pk_fma_f32 v[78:79], v[78:79], v[142:143], v[158:159]
	v_cvt_pk_bf16_f32 v64, v64, v65
	v_cvt_pk_bf16_f32 v65, v66, v67
	v_cvt_pk_bf16_f32 v66, v68, v69
	v_cvt_pk_bf16_f32 v67, v70, v71
	v_cvt_pk_bf16_f32 v68, v72, v73
	v_cvt_pk_bf16_f32 v69, v74, v75
	v_cvt_pk_bf16_f32 v70, v76, v77
	v_cvt_pk_bf16_f32 v71, v78, v79
	s_lshl_b32 s99, s98, 11
	v_lshl_add_u32 v8, v0, 3, s99
	global_store_dwordx2 v8, v[64:65], s[94:95]
	global_store_dwordx2 v8, v[66:67], s[94:95] offset:512
	global_store_dwordx2 v8, v[68:69], s[94:95] offset:1024
	global_store_dwordx2 v8, v[70:71], s[94:95] offset:1536
	s_lshl_b32 s99, s98, 2
	v_mov_b32_e32 v9, s99
	v_mov_b32_e32 v10, 0
	v_cmp_eq_u32_e32 vcc, 0, v0
	s_and_saveexec_b64 s[98:99], vcc
	global_store_dword v9, v10, s[90:91]
	global_store_dword v9, v10, s[92:93]
	s_or_b64 exec, exec, s[98:99]
	s_waitcnt vmcnt(0)
.Lnp1_done:
	v_mbcnt_hi_u32_b32 v32, -1, v210
	s_mov_b64 s[4:5], exec
	s_cmp_eq_u32 s80, 2
	s_cbranch_scc1 .Lp1_end

.LBB0_241:
	s_cmp_eq_u32 s80, 1
	s_cbranch_scc0 .Lp1_end
	s_mov_b32 s80, 2
	s_mov_b64 exec, -1
	s_branch .Lp1_norm_first
